# full grid barriers: the XCD leader bumps its XCD's release generation before doing its own L1+L2 invalidate (each released workgroup still does its own acquire)
# speedup vs baseline: 1.0085x; 1.0085x over previous
.LBB0_144:
	s_or_b64 exec, exec, s[10:11]
	s_mov_b64 s[6:7], exec
	v_mbcnt_lo_u32_b32 v0, s6, 0
	v_mbcnt_hi_u32_b32 v0, s7, v0
	v_cmp_eq_u32_e32 vcc, 0, v0
	s_waitcnt vmcnt(0)
	s_and_saveexec_b64 s[10:11], vcc
	s_cbranch_execz .LBB0_146
	s_bcnt1_i32_b64 s0, s[6:7]
	v_mov_b32_e32 v0, 0x2000
	v_mov_b32_e32 v1, s0
	global_atomic_add v0, v1, s[8:9] offset:1024
.LBB0_146:
	s_or_b64 exec, exec, s[10:11]
	buffer_inv sc1
	s_waitcnt vmcnt(0)

.LBB0_150:
	s_or_b64 exec, exec, s[12:13]
	v_readlane_b32 s2, v255, 40
	s_nop 0
	s_cmp_lg_u32 s2, 0
	s_cbranch_scc0 .Linvf_b2j
	s_cmp_lg_u64 s[10:11], 0
	s_cbranch_scc0 .Linvf_b2j
	buffer_inv sc0
	s_branch .Linvd_b2j

.Linvd_b2j:
	s_waitcnt vmcnt(0)
.LBB0_151:
	s_or_b64 exec, exec, s[4:5]
	s_mov_b32 s56, 1
	s_mov_b64 s[58:59], 0
	s_mov_b64 s[4:5], -1
	s_and_b64 vcc, exec, s[10:11]
	s_waitcnt lgkmcnt(0)
	s_barrier
	s_cbranch_vccnz .LBB0_148

.LBB0_233:
	s_or_b64 exec, exec, s[10:11]
	s_mov_b64 s[6:7], exec
	v_mbcnt_lo_u32_b32 v0, s6, 0
	v_mbcnt_hi_u32_b32 v0, s7, v0
	v_cmp_eq_u32_e32 vcc, 0, v0
	s_waitcnt vmcnt(0)
	s_and_saveexec_b64 s[10:11], vcc
	s_cbranch_execz .LBB0_235
	s_bcnt1_i32_b64 s2, s[6:7]
	v_mov_b32_e32 v0, s2
	global_atomic_add v231, v0, s[8:9] offset:1024

.LBB0_1373:
	s_or_b64 exec, exec, s[12:13]
	s_mov_b64 s[6:7], exec
	v_mbcnt_lo_u32_b32 v0, s6, 0
	v_mbcnt_hi_u32_b32 v0, s7, v0
	v_cmp_eq_u32_e32 vcc, 0, v0
	s_waitcnt vmcnt(0)
	s_and_saveexec_b64 s[12:13], vcc
	s_cbranch_execnz .LBB0_1374
	s_getpc_b64 s[98:99]
